# A-tile global loads interleaved between MFMAs too; resid units remapped to XCD-local 8x8 patches; DSA QK kb0 LDS reads pipelined
# speedup vs baseline: 1.0122x; 1.0122x over previous
.Lg1_head:
	s_cmpk_gt_u32 s27, 0x7bf
	s_waitcnt vmcnt(0)
	ds_write_b128 v205, v[134:137]
	ds_write_b128 v205, v[130:133] offset:4096
	ds_write_b128 v205, v[142:145] offset:8192
	ds_write_b128 v205, v[138:141] offset:12288
	ds_write_b128 v205, v[146:149] offset:16384
	ds_write_b128 v205, v[150:153] offset:20480
	ds_write_b128 v205, v[154:157] offset:24576
	ds_write_b128 v205, v[158:161] offset:28672
	ds_write_b128 v205, v[162:165] offset:32768
	ds_write_b128 v205, v[166:169] offset:36864
	ds_write_b128 v205, v[170:173] offset:40960
	ds_write_b128 v205, v[174:177] offset:45056
	s_waitcnt lgkmcnt(0)
	s_barrier
	s_cbranch_scc1 .Lg1_final
	s_add_i32 s27, s27, 64
	ds_read_b128 v[178:181], v207
	ds_read_b128 v[182:185], v207 offset:4096
	ds_read_b128 v[194:197], v236 offset:16384
	ds_read_b128 v[198:201], v236 offset:20480
	ds_read_b128 v[228:231], v236 offset:24576
	s_setprio 1
	s_waitcnt lgkmcnt(2)
	v_mfma_f32_32x32x16_bf16 v[114:129], v[178:181], v[194:197], v[114:129]
	v_mfma_f32_32x32x16_bf16 v[50:65], v[182:185], v[194:197], v[50:65]
	ds_read_b128 v[194:197], v236 offset:28672
	ds_read_b128 v[186:189], v223
	s_and_b64 exec, vcc, s[4:5]
	global_load_dwordx4 v[134:137], v202, s[28:29]
	s_mov_b64 exec, vcc
	s_waitcnt lgkmcnt(3)
	v_mfma_f32_32x32x16_bf16 v[98:113], v[178:181], v[198:201], v[98:113]
	v_mfma_f32_32x32x16_bf16 v[34:49], v[182:185], v[198:201], v[34:49]
	ds_read_b128 v[198:201], v237 offset:16384
	ds_read_b128 v[190:193], v223 offset:4096
	s_and_b64 exec, vcc, s[6:7]
	global_load_dwordx4 v[130:133], v203, s[28:29]
	s_mov_b64 exec, vcc
	s_waitcnt lgkmcnt(4)
	v_mfma_f32_32x32x16_bf16 v[82:97], v[178:181], v[228:231], v[82:97]
	v_mfma_f32_32x32x16_bf16 v[18:33], v[182:185], v[228:231], v[18:33]
	ds_read_b128 v[228:231], v237 offset:20480
	s_and_b64 exec, vcc, s[8:9]
	global_load_dwordx4 v[142:145], v210, s[28:29]
	s_mov_b64 exec, vcc
	s_waitcnt lgkmcnt(4)
	v_mfma_f32_32x32x16_bf16 v[66:81], v[178:181], v[194:197], v[66:81]
	v_mfma_f32_32x32x16_bf16 v[2:17], v[182:185], v[194:197], v[2:17]
	ds_read_b128 v[194:197], v237 offset:24576
	s_and_b64 exec, vcc, s[10:11]
	global_load_dwordx4 v[138:141], v232, s[28:29]
	s_mov_b64 exec, vcc
	s_add_u32 s28, s28, 0x80
	s_addc_u32 s29, s29, 0
	s_waitcnt lgkmcnt(2)
	v_mfma_f32_32x32x16_bf16 v[114:129], v[186:189], v[198:201], v[114:129]
	v_mfma_f32_32x32x16_bf16 v[50:65], v[190:193], v[198:201], v[50:65]
	ds_read_b128 v[198:201], v237 offset:28672
	ds_read_b128 v[178:181], v225
	global_load_dwordx4 v[146:149], v233, s[100:101]
	s_waitcnt lgkmcnt(3)
	v_mfma_f32_32x32x16_bf16 v[98:113], v[186:189], v[228:231], v[98:113]
	v_mfma_f32_32x32x16_bf16 v[34:49], v[190:193], v[228:231], v[34:49]
	ds_read_b128 v[228:231], v238 offset:16384
	ds_read_b128 v[182:185], v225 offset:4096
	v_add_u32_e32 v234, 0x20000, v233
	global_load_dwordx4 v[150:153], v234, s[100:101]
	s_waitcnt lgkmcnt(4)
	v_mfma_f32_32x32x16_bf16 v[82:97], v[186:189], v[194:197], v[82:97]
	v_mfma_f32_32x32x16_bf16 v[18:33], v[190:193], v[194:197], v[18:33]
	ds_read_b128 v[194:197], v238 offset:20480
	v_add_u32_e32 v235, 0x40000, v233
	global_load_dwordx4 v[154:157], v235, s[100:101]
	s_waitcnt lgkmcnt(4)
	v_mfma_f32_32x32x16_bf16 v[66:81], v[186:189], v[198:201], v[66:81]
	v_mfma_f32_32x32x16_bf16 v[2:17], v[190:193], v[198:201], v[2:17]
	ds_read_b128 v[198:201], v238 offset:24576
	v_add_u32_e32 v234, 0x60000, v233
	global_load_dwordx4 v[158:161], v234, s[100:101]
	s_waitcnt lgkmcnt(2)
	v_mfma_f32_32x32x16_bf16 v[114:129], v[178:181], v[228:231], v[114:129]
	v_mfma_f32_32x32x16_bf16 v[50:65], v[182:185], v[228:231], v[50:65]
	ds_read_b128 v[228:231], v238 offset:28672
	ds_read_b128 v[186:189], v226
	v_add_u32_e32 v235, 0x80000, v233
	global_load_dwordx4 v[162:165], v235, s[100:101]
	s_waitcnt lgkmcnt(3)
	v_mfma_f32_32x32x16_bf16 v[98:113], v[178:181], v[194:197], v[98:113]
	v_mfma_f32_32x32x16_bf16 v[34:49], v[182:185], v[194:197], v[34:49]
	ds_read_b128 v[194:197], v239 offset:16384
	ds_read_b128 v[190:193], v226 offset:4096
	v_add_u32_e32 v234, 0xa0000, v233
	global_load_dwordx4 v[166:169], v234, s[100:101]
	s_waitcnt lgkmcnt(4)
	v_mfma_f32_32x32x16_bf16 v[82:97], v[178:181], v[198:201], v[82:97]
	v_mfma_f32_32x32x16_bf16 v[18:33], v[182:185], v[198:201], v[18:33]
	ds_read_b128 v[198:201], v239 offset:20480
	v_add_u32_e32 v235, 0xc0000, v233
	global_load_dwordx4 v[170:173], v235, s[100:101]
	s_waitcnt lgkmcnt(4)
	v_mfma_f32_32x32x16_bf16 v[66:81], v[178:181], v[228:231], v[66:81]
	v_mfma_f32_32x32x16_bf16 v[2:17], v[182:185], v[228:231], v[2:17]
	ds_read_b128 v[228:231], v239 offset:24576
	v_add_u32_e32 v234, 0xe0000, v233
	global_load_dwordx4 v[174:177], v234, s[100:101]
	s_add_u32 s100, s100, 0x80
	s_addc_u32 s101, s101, 0
	s_waitcnt lgkmcnt(2)
	v_mfma_f32_32x32x16_bf16 v[114:129], v[186:189], v[194:197], v[114:129]
	v_mfma_f32_32x32x16_bf16 v[50:65], v[190:193], v[194:197], v[50:65]
	ds_read_b128 v[194:197], v239 offset:28672
	s_waitcnt lgkmcnt(2)
	v_mfma_f32_32x32x16_bf16 v[98:113], v[186:189], v[198:201], v[98:113]
	v_mfma_f32_32x32x16_bf16 v[34:49], v[190:193], v[198:201], v[34:49]
	s_waitcnt lgkmcnt(1)
	v_mfma_f32_32x32x16_bf16 v[82:97], v[186:189], v[228:231], v[82:97]
	v_mfma_f32_32x32x16_bf16 v[18:33], v[190:193], v[228:231], v[18:33]
	s_waitcnt lgkmcnt(0)
	v_mfma_f32_32x32x16_bf16 v[66:81], v[186:189], v[194:197], v[66:81]
	v_mfma_f32_32x32x16_bf16 v[2:17], v[190:193], v[194:197], v[2:17]
	s_setprio 0
	s_barrier
	s_branch .Lg1_head

.LBB0_762:
	v_cmp_gt_i32_e32 vcc, s35, v183
	s_setprio 1
	ds_read_b128 v[4:7], v226
	ds_read_b128 v[96:99], v226 offset:32
	ds_read_b128 v[100:103], v226 offset:64
	ds_read_b128 v[104:107], v226 offset:96
	ds_read_b128 v[108:111], v226 offset:128
	s_waitcnt lgkmcnt(4)
	v_mfma_f32_32x32x16_bf16 v[80:95], v[4:7], v[112:115], 0
	ds_read_b128 v[4:7], v226 offset:160
	s_waitcnt lgkmcnt(4)
	v_mfma_f32_32x32x16_bf16 v[80:95], v[96:99], v[116:119], v[80:95]
	ds_read_b128 v[96:99], v226 offset:192
	s_waitcnt lgkmcnt(4)
	v_mfma_f32_32x32x16_bf16 v[80:95], v[100:103], v[120:123], v[80:95]
	ds_read_b128 v[100:103], v226 offset:224
	s_waitcnt lgkmcnt(4)
	v_mfma_f32_32x32x16_bf16 v[80:95], v[104:107], v[124:127], v[80:95]
	s_waitcnt lgkmcnt(3)
	v_mfma_f32_32x32x16_bf16 v[80:95], v[108:111], v[128:131], v[80:95]
	s_waitcnt lgkmcnt(2)
	v_mfma_f32_32x32x16_bf16 v[80:95], v[4:7], v[132:135], v[80:95]
	s_waitcnt lgkmcnt(1)
	v_mfma_f32_32x32x16_bf16 v[80:95], v[96:99], v[136:139], v[80:95]
	s_waitcnt lgkmcnt(0)
	v_mfma_f32_32x32x16_bf16 v[80:95], v[100:103], v[140:143], v[80:95]
	s_setprio 0
	v_add_u32_e32 v1, 32, v183
	v_lshrrev_b64 v[4:5], v196, v[202:203]
	v_cmp_gt_i32_e64 s[4:5], s35, v1
	s_and_saveexec_b64 s[2:3], s[4:5]
	s_xor_b64 s[2:3], exec, s[2:3]
	s_cbranch_execz .LBB0_781
	v_add3_u32 v1, v205, v183, 63
	v_mov_b32_e32 v5, v179
	s_and_saveexec_b64 s[6:7], vcc
	s_cbranch_execnz .LBB0_801
	s_or_b64 exec, exec, s[6:7]
	v_mov_b32_e32 v6, v179
	s_and_saveexec_b64 s[6:7], vcc
	s_cbranch_execnz .LBB0_802

.Lg2_head:
	s_cmpk_gt_u32 s29, 0x7bf
	s_waitcnt vmcnt(0)
	ds_write_b128 v205, v[134:137]
	ds_write_b128 v205, v[130:133] offset:4096
	ds_write_b128 v205, v[142:145] offset:8192
	ds_write_b128 v205, v[138:141] offset:12288
	ds_write_b128 v205, v[146:149] offset:16384
	ds_write_b128 v205, v[150:153] offset:20480
	ds_write_b128 v205, v[154:157] offset:24576
	ds_write_b128 v205, v[158:161] offset:28672
	ds_write_b128 v205, v[162:165] offset:32768
	ds_write_b128 v205, v[166:169] offset:36864
	ds_write_b128 v205, v[170:173] offset:40960
	ds_write_b128 v205, v[174:177] offset:45056
	s_waitcnt lgkmcnt(0)
	s_barrier
	s_cbranch_scc1 .Lg2_final
	s_add_i32 s29, s29, 64
	ds_read_b128 v[178:181], v207
	ds_read_b128 v[182:185], v207 offset:4096
	ds_read_b128 v[194:197], v236 offset:16384
	ds_read_b128 v[198:201], v236 offset:20480
	ds_read_b128 v[228:231], v236 offset:24576
	s_setprio 1
	s_waitcnt lgkmcnt(2)
	v_mfma_f32_32x32x16_bf16 v[114:129], v[178:181], v[194:197], v[114:129]
	v_mfma_f32_32x32x16_bf16 v[50:65], v[182:185], v[194:197], v[50:65]
	ds_read_b128 v[194:197], v236 offset:28672
	ds_read_b128 v[186:189], v223
	s_and_b64 exec, vcc, s[6:7]
	global_load_dwordx4 v[134:137], v202, s[4:5]
	s_mov_b64 exec, vcc
	s_waitcnt lgkmcnt(3)
	v_mfma_f32_32x32x16_bf16 v[98:113], v[178:181], v[198:201], v[98:113]
	v_mfma_f32_32x32x16_bf16 v[34:49], v[182:185], v[198:201], v[34:49]
	ds_read_b128 v[198:201], v237 offset:16384
	ds_read_b128 v[190:193], v223 offset:4096
	s_and_b64 exec, vcc, s[8:9]
	global_load_dwordx4 v[130:133], v203, s[4:5]
	s_mov_b64 exec, vcc
	s_waitcnt lgkmcnt(4)
	v_mfma_f32_32x32x16_bf16 v[82:97], v[178:181], v[228:231], v[82:97]
	v_mfma_f32_32x32x16_bf16 v[18:33], v[182:185], v[228:231], v[18:33]
	ds_read_b128 v[228:231], v237 offset:20480
	s_and_b64 exec, vcc, s[10:11]
	global_load_dwordx4 v[142:145], v210, s[4:5]
	s_mov_b64 exec, vcc
	s_waitcnt lgkmcnt(4)
	v_mfma_f32_32x32x16_bf16 v[66:81], v[178:181], v[194:197], v[66:81]
	v_mfma_f32_32x32x16_bf16 v[2:17], v[182:185], v[194:197], v[2:17]
	ds_read_b128 v[194:197], v237 offset:24576
	s_and_b64 exec, vcc, s[12:13]
	global_load_dwordx4 v[138:141], v232, s[4:5]
	s_mov_b64 exec, vcc
	s_add_u32 s4, s4, 0x80
	s_addc_u32 s5, s5, 0
	s_waitcnt lgkmcnt(2)
	v_mfma_f32_32x32x16_bf16 v[114:129], v[186:189], v[198:201], v[114:129]
	v_mfma_f32_32x32x16_bf16 v[50:65], v[190:193], v[198:201], v[50:65]
	ds_read_b128 v[198:201], v237 offset:28672
	ds_read_b128 v[178:181], v225
	global_load_dwordx4 v[146:149], v233, s[100:101]
	s_waitcnt lgkmcnt(3)
	v_mfma_f32_32x32x16_bf16 v[98:113], v[186:189], v[228:231], v[98:113]
	v_mfma_f32_32x32x16_bf16 v[34:49], v[190:193], v[228:231], v[34:49]
	ds_read_b128 v[228:231], v238 offset:16384
	ds_read_b128 v[182:185], v225 offset:4096
	v_add_u32_e32 v234, 0x20000, v233
	global_load_dwordx4 v[150:153], v234, s[100:101]
	s_waitcnt lgkmcnt(4)
	v_mfma_f32_32x32x16_bf16 v[82:97], v[186:189], v[194:197], v[82:97]
	v_mfma_f32_32x32x16_bf16 v[18:33], v[190:193], v[194:197], v[18:33]
	ds_read_b128 v[194:197], v238 offset:20480
	v_add_u32_e32 v235, 0x40000, v233
	global_load_dwordx4 v[154:157], v235, s[100:101]
	s_waitcnt lgkmcnt(4)
	v_mfma_f32_32x32x16_bf16 v[66:81], v[186:189], v[198:201], v[66:81]
	v_mfma_f32_32x32x16_bf16 v[2:17], v[190:193], v[198:201], v[2:17]
	ds_read_b128 v[198:201], v238 offset:24576
	v_add_u32_e32 v234, 0x60000, v233
	global_load_dwordx4 v[158:161], v234, s[100:101]
	s_waitcnt lgkmcnt(2)
	v_mfma_f32_32x32x16_bf16 v[114:129], v[178:181], v[228:231], v[114:129]
	v_mfma_f32_32x32x16_bf16 v[50:65], v[182:185], v[228:231], v[50:65]
	ds_read_b128 v[228:231], v238 offset:28672
	ds_read_b128 v[186:189], v226
	v_add_u32_e32 v235, 0x80000, v233
	global_load_dwordx4 v[162:165], v235, s[100:101]
	s_waitcnt lgkmcnt(3)
	v_mfma_f32_32x32x16_bf16 v[98:113], v[178:181], v[194:197], v[98:113]
	v_mfma_f32_32x32x16_bf16 v[34:49], v[182:185], v[194:197], v[34:49]
	ds_read_b128 v[194:197], v239 offset:16384
	ds_read_b128 v[190:193], v226 offset:4096
	v_add_u32_e32 v234, 0xa0000, v233
	global_load_dwordx4 v[166:169], v234, s[100:101]
	s_waitcnt lgkmcnt(4)
	v_mfma_f32_32x32x16_bf16 v[82:97], v[178:181], v[198:201], v[82:97]
	v_mfma_f32_32x32x16_bf16 v[18:33], v[182:185], v[198:201], v[18:33]
	ds_read_b128 v[198:201], v239 offset:20480
	v_add_u32_e32 v235, 0xc0000, v233
	global_load_dwordx4 v[170:173], v235, s[100:101]
	s_waitcnt lgkmcnt(4)
	v_mfma_f32_32x32x16_bf16 v[66:81], v[178:181], v[228:231], v[66:81]
	v_mfma_f32_32x32x16_bf16 v[2:17], v[182:185], v[228:231], v[2:17]
	ds_read_b128 v[228:231], v239 offset:24576
	v_add_u32_e32 v234, 0xe0000, v233
	global_load_dwordx4 v[174:177], v234, s[100:101]
	s_add_u32 s100, s100, 0x80
	s_addc_u32 s101, s101, 0
	s_waitcnt lgkmcnt(2)
	v_mfma_f32_32x32x16_bf16 v[114:129], v[186:189], v[194:197], v[114:129]
	v_mfma_f32_32x32x16_bf16 v[50:65], v[190:193], v[194:197], v[50:65]
	ds_read_b128 v[194:197], v239 offset:28672
	s_waitcnt lgkmcnt(2)
	v_mfma_f32_32x32x16_bf16 v[98:113], v[186:189], v[198:201], v[98:113]
	v_mfma_f32_32x32x16_bf16 v[34:49], v[190:193], v[198:201], v[34:49]
	s_waitcnt lgkmcnt(1)
	v_mfma_f32_32x32x16_bf16 v[82:97], v[186:189], v[228:231], v[82:97]
	v_mfma_f32_32x32x16_bf16 v[18:33], v[190:193], v[228:231], v[18:33]
	s_waitcnt lgkmcnt(0)
	v_mfma_f32_32x32x16_bf16 v[66:81], v[186:189], v[194:197], v[66:81]
	v_mfma_f32_32x32x16_bf16 v[2:17], v[190:193], v[194:197], v[2:17]
	s_setprio 0
	s_barrier
	s_branch .Lg2_head

.LBB0_1946:
	v_mov_b32_e32 v14, v208
	s_and_b32 s100, s38, 7
	s_lshl_b32 s100, s100, 6
	s_bfe_u32 s101, s38, 0x60003
	s_or_b32 s100, s100, s101
	s_and_b32 s101, s38, 0x200
	s_or_b32 s100, s100, s101
	s_lshl_b32 s4, s100, 4
	v_lshlrev_b32_e32 v15, 3, v14
	v_and_b32_e32 v2, 56, v15
	s_and_b32 s20, s4, 0xffffff80
	v_lshlrev_b32_e32 v8, 1, v2
	v_ashrrev_i32_e32 v2, 3, v14
	v_mov_b32_e32 v9, v0
	v_add_u32_e32 v3, s20, v2
	v_lshl_add_u64 v[12:13], s[0:1], 0, v[8:9]
	v_cmp_gt_u32_e64 s[4:5], s50, v3
	v_mov_b32_e32 v130, 0
	v_mov_b32_e32 v134, 0
	v_mov_b32_e32 v135, 0
	v_mov_b32_e32 v136, 0
	v_mov_b32_e32 v137, 0
	s_and_saveexec_b64 s[6:7], s[4:5]
	s_cbranch_execz .LBB0_1948
	v_lshlrev_b32_e32 v4, 12, v3
	v_mov_b32_e32 v5, v0
	v_lshl_add_u64 v[4:5], v[12:13], 0, v[4:5]
	global_load_dwordx4 v[134:137], v[4:5], off

.LBB0_1954:
	s_or_b64 exec, exec, s[20:21]
	s_and_b32 s100, s38, 7
	s_lshl_b32 s100, s100, 6
	s_bfe_u32 s101, s38, 0x60003
	s_or_b32 s100, s100, s101
	s_and_b32 s101, s38, 0x200
	s_or_b32 s100, s100, s101
	s_lshl_b32 s22, s100, 8
	s_lshl_b32 s20, s100, 4
	s_and_b32 s20, s20, 0xffffff80
	s_lshl_b32 s21, s100, 20
	s_and_b32 s39, s22, 0x700
	s_mov_b32 s40, s100
	s_and_b32 s26, s21, 0x700000
	s_ashr_i32 s21, s20, 31
	s_lshl_b32 s22, s39, 12
	s_add_u32 s22, s24, s22
	s_addc_u32 s23, s28, 0
	v_mov_b32_e32 v9, v0
	v_ashrrev_i32_e32 v3, 31, v2
	v_lshl_add_u64 v[8:9], s[22:23], 0, v[8:9]
	v_lshlrev_b64 v[12:13], 12, v[2:3]
	v_ashrrev_i32_e32 v5, 31, v4
	v_lshl_add_u64 v[16:17], v[8:9], 0, v[12:13]
	v_lshlrev_b64 v[18:19], 12, v[4:5]
	v_ashrrev_i32_e32 v7, 31, v6
	v_lshl_add_u64 v[20:21], v[8:9], 0, v[18:19]
	global_load_dwordx4 v[146:149], v[16:17], off
	global_load_dwordx4 v[150:153], v[20:21], off
	v_lshlrev_b64 v[16:17], 12, v[6:7]
	v_ashrrev_i32_e32 v11, 31, v10
	v_lshl_add_u64 v[20:21], v[8:9], 0, v[16:17]
	v_lshlrev_b64 v[22:23], 12, v[10:11]
	v_lshl_add_u64 v[24:25], v[8:9], 0, v[22:23]
	global_load_dwordx4 v[154:157], v[20:21], off
	global_load_dwordx4 v[158:161], v[24:25], off
	v_add_u32_e32 v20, 0x400, v14
	v_ashrrev_i32_e32 v20, 3, v20
	v_add_u32_e32 v26, 0x500, v14
	v_ashrrev_i32_e32 v21, 31, v20
	v_ashrrev_i32_e32 v26, 3, v26
	v_lshlrev_b64 v[20:21], 12, v[20:21]
	v_ashrrev_i32_e32 v27, 31, v26
	v_lshl_add_u64 v[24:25], v[8:9], 0, v[20:21]
	v_lshlrev_b64 v[26:27], 12, v[26:27]
	v_lshl_add_u64 v[28:29], v[8:9], 0, v[26:27]
	global_load_dwordx4 v[162:165], v[24:25], off
	global_load_dwordx4 v[166:169], v[28:29], off
	v_add_u32_e32 v24, 0x600, v14
	v_ashrrev_i32_e32 v24, 3, v24
	v_add_u32_e32 v30, 0x700, v14
	v_ashrrev_i32_e32 v25, 31, v24
	v_ashrrev_i32_e32 v30, 3, v30
	v_lshlrev_b64 v[24:25], 12, v[24:25]
	v_ashrrev_i32_e32 v31, 31, v30
	v_lshl_add_u64 v[28:29], v[8:9], 0, v[24:25]
	v_lshlrev_b64 v[30:31], 12, v[30:31]
	v_lshl_add_u64 v[8:9], v[8:9], 0, v[30:31]
	global_load_dwordx4 v[170:173], v[28:29], off
	global_load_dwordx4 v[174:177], v[8:9], off
	v_lshrrev_b32_e32 v9, 4, v14
	v_xor_b32_e32 v9, v9, v14
	v_and_b32_e32 v15, 0x7fffffc0, v15
	v_lshrrev_b32_e32 v33, 5, v14
	v_lshlrev_b32_e32 v9, 4, v9
	v_bfe_u32 v29, v14, 1, 3
	v_lshlrev_b32_e32 v15, 1, v15
	v_and_b32_e32 v32, 31, v14
	v_bfe_u32 v8, v14, 5, 1
	v_lshrrev_b32_e32 v28, 1, v14
	v_lshlrev_b32_e32 v34, 1, v14
	v_and_or_b32 v222, v9, s45, v15
	v_bitop3_b32 v9, v33, v29, 1 bitop3:0x6c
	v_and_or_b32 v28, v28, s87, v32
	v_and_or_b32 v32, v34, s35, v32
	v_bitop3_b32 v34, v8, v29, 6 bitop3:0x36
	v_lshlrev_b32_e32 v223, 4, v9
	v_bitop3_b32 v9, v8, v29, 2 bitop3:0x36
	v_bitop3_b32 v8, v8, v29, 4 bitop3:0x36
	v_lshlrev_b32_e32 v227, 4, v8
	v_and_b32_e32 v8, 7, v14
	v_lshl_add_u64 v[2:3], v[2:3], 0, s[20:21]
	v_lshlrev_b32_e32 v225, 4, v9
	v_lshlrev_b32_e32 v178, 4, v8
	s_add_u32 s22, s29, s26
	v_lshl_add_u64 v[8:9], v[10:11], 0, s[20:21]
	v_lshl_add_u64 v[6:7], v[6:7], 0, s[20:21]
	v_lshl_add_u64 v[4:5], v[4:5], 0, s[20:21]
	v_lshlrev_b64 v[2:3], 12, v[2:3]
	v_lshlrev_b32_e32 v28, 7, v28
	v_lshlrev_b32_e32 v206, 4, v34
	s_addc_u32 s23, s30, 0
	v_lshlrev_b64 v[8:9], 12, v[8:9]
	v_lshlrev_b64 v[6:7], 12, v[6:7]
	v_lshlrev_b64 v[4:5], 12, v[4:5]
	v_lshl_add_u64 v[202:203], s[14:15], 0, v[2:3]
	v_mov_b32_e32 v2, 0
	v_lshlrev_b32_e32 v207, 7, v32
	v_or_b32_e32 v224, v28, v223
	v_or_b32_e32 v226, v28, v225
	v_or_b32_e32 v228, v28, v227
	v_or_b32_e32 v229, v28, v206
	v_mov_b32_e32 v179, v0
	v_lshl_add_u64 v[180:181], s[22:23], 0, v[30:31]
	v_lshl_add_u64 v[182:183], s[22:23], 0, v[24:25]
	v_lshl_add_u64 v[184:185], s[22:23], 0, v[26:27]
	v_lshl_add_u64 v[186:187], s[22:23], 0, v[20:21]
	v_lshl_add_u64 v[188:189], s[22:23], 0, v[22:23]
	v_lshl_add_u64 v[190:191], s[22:23], 0, v[16:17]
	v_lshl_add_u64 v[192:193], s[22:23], 0, v[18:19]
	v_lshl_add_u64 v[194:195], s[22:23], 0, v[12:13]
	v_lshl_add_u64 v[196:197], s[14:15], 0, v[8:9]
	v_lshl_add_u64 v[198:199], s[14:15], 0, v[6:7]
	v_lshl_add_u64 v[200:201], s[14:15], 0, v[4:5]
	s_mov_b32 s21, 0
	v_mov_b32_e32 v3, v2
	v_mov_b32_e32 v4, v2
	v_mov_b32_e32 v5, v2
	v_mov_b32_e32 v6, v2
	v_mov_b32_e32 v7, v2
	v_mov_b32_e32 v8, v2
	v_mov_b32_e32 v9, v2
	v_mov_b32_e32 v10, v2
	v_mov_b32_e32 v11, v2
	v_mov_b32_e32 v12, v2
	v_mov_b32_e32 v13, v2
	v_mov_b32_e32 v14, v2
	v_mov_b32_e32 v15, v2
	v_mov_b32_e32 v16, v2
	v_mov_b32_e32 v17, v2
	v_mov_b32_e32 v18, v2
	v_mov_b32_e32 v19, v2
	v_mov_b32_e32 v20, v2
	v_mov_b32_e32 v21, v2
	v_mov_b32_e32 v22, v2
	v_mov_b32_e32 v23, v2
	v_mov_b32_e32 v24, v2
	v_mov_b32_e32 v25, v2
	v_mov_b32_e32 v26, v2
	v_mov_b32_e32 v27, v2
	v_mov_b32_e32 v28, v2
	v_mov_b32_e32 v29, v2
	v_mov_b32_e32 v30, v2
	v_mov_b32_e32 v31, v2
	v_mov_b32_e32 v32, v2
	v_mov_b32_e32 v33, v2
	v_mov_b32_e32 v34, v2
	v_mov_b32_e32 v35, v2
	v_mov_b32_e32 v36, v2
	v_mov_b32_e32 v37, v2
	v_mov_b32_e32 v38, v2
	v_mov_b32_e32 v39, v2
	v_mov_b32_e32 v40, v2
	v_mov_b32_e32 v41, v2
	v_mov_b32_e32 v42, v2
	v_mov_b32_e32 v43, v2
	v_mov_b32_e32 v44, v2
	v_mov_b32_e32 v45, v2
	v_mov_b32_e32 v46, v2
	v_mov_b32_e32 v47, v2
	v_mov_b32_e32 v48, v2
	v_mov_b32_e32 v49, v2
	v_mov_b32_e32 v50, v2
	v_mov_b32_e32 v51, v2
	v_mov_b32_e32 v52, v2
	v_mov_b32_e32 v53, v2
	v_mov_b32_e32 v54, v2
	v_mov_b32_e32 v55, v2
	v_mov_b32_e32 v56, v2
	v_mov_b32_e32 v57, v2
	v_mov_b32_e32 v58, v2
	v_mov_b32_e32 v59, v2
	v_mov_b32_e32 v60, v2
	v_mov_b32_e32 v61, v2
	v_mov_b32_e32 v62, v2
	v_mov_b32_e32 v63, v2
	v_mov_b32_e32 v64, v2
	v_mov_b32_e32 v65, v2
	v_mov_b32_e32 v66, v2
	v_mov_b32_e32 v67, v2
	v_mov_b32_e32 v68, v2
	v_mov_b32_e32 v69, v2
	v_mov_b32_e32 v70, v2
	v_mov_b32_e32 v71, v2
	v_mov_b32_e32 v72, v2
	v_mov_b32_e32 v73, v2
	v_mov_b32_e32 v74, v2
	v_mov_b32_e32 v75, v2
	v_mov_b32_e32 v76, v2
	v_mov_b32_e32 v77, v2
	v_mov_b32_e32 v78, v2
	v_mov_b32_e32 v79, v2
	v_mov_b32_e32 v80, v2
	v_mov_b32_e32 v81, v2
	v_mov_b32_e32 v82, v2
	v_mov_b32_e32 v83, v2
	v_mov_b32_e32 v84, v2
	v_mov_b32_e32 v85, v2
	v_mov_b32_e32 v86, v2
	v_mov_b32_e32 v87, v2
	v_mov_b32_e32 v88, v2
	v_mov_b32_e32 v89, v2
	v_mov_b32_e32 v90, v2
	v_mov_b32_e32 v91, v2
	v_mov_b32_e32 v92, v2
	v_mov_b32_e32 v93, v2
	v_mov_b32_e32 v94, v2
	v_mov_b32_e32 v95, v2
	v_mov_b32_e32 v96, v2
	v_mov_b32_e32 v97, v2
	v_mov_b32_e32 v98, v2
	v_mov_b32_e32 v99, v2
	v_mov_b32_e32 v100, v2
	v_mov_b32_e32 v101, v2
	v_mov_b32_e32 v102, v2
	v_mov_b32_e32 v103, v2
	v_mov_b32_e32 v104, v2
	v_mov_b32_e32 v105, v2
	v_mov_b32_e32 v106, v2
	v_mov_b32_e32 v107, v2
	v_mov_b32_e32 v108, v2
	v_mov_b32_e32 v109, v2
	v_mov_b32_e32 v110, v2
	v_mov_b32_e32 v111, v2
	v_mov_b32_e32 v112, v2
	v_mov_b32_e32 v113, v2
	v_mov_b32_e32 v114, v2
	v_mov_b32_e32 v115, v2
	v_mov_b32_e32 v116, v2
	v_mov_b32_e32 v117, v2
	v_mov_b32_e32 v118, v2
	v_mov_b32_e32 v119, v2
	v_mov_b32_e32 v120, v2
	v_mov_b32_e32 v121, v2
	v_mov_b32_e32 v122, v2
	v_mov_b32_e32 v123, v2
	v_mov_b32_e32 v124, v2
	v_mov_b32_e32 v125, v2
	v_mov_b32_e32 v126, v2
	v_mov_b32_e32 v127, v2
	v_mov_b32_e32 v128, v2
	v_mov_b32_e32 v129, v2
	s_branch .Lg3_pre

.Lg3_head:
	s_cmpk_gt_u32 s21, 0x7bf
	s_waitcnt vmcnt(0)
	ds_write_b128 v222, v[134:137]
	ds_write_b128 v222, v[130:133] offset:4096
	ds_write_b128 v222, v[142:145] offset:8192
	ds_write_b128 v222, v[138:141] offset:12288
	ds_write_b128 v222, v[146:149] offset:16384
	ds_write_b128 v222, v[150:153] offset:20480
	ds_write_b128 v222, v[154:157] offset:24576
	ds_write_b128 v222, v[158:161] offset:28672
	ds_write_b128 v222, v[162:165] offset:32768
	ds_write_b128 v222, v[166:169] offset:36864
	ds_write_b128 v222, v[170:173] offset:40960
	ds_write_b128 v222, v[174:177] offset:45056
	s_waitcnt lgkmcnt(0)
	s_barrier
	s_cbranch_scc1 .Lg3_final
	s_add_i32 s21, s21, 64
	ds_read_b128 v[178:181], v224
	ds_read_b128 v[182:185], v224 offset:4096
	ds_read_b128 v[194:197], v235 offset:16384
	ds_read_b128 v[198:201], v235 offset:20480
	ds_read_b128 v[210:213], v235 offset:24576
	s_setprio 1
	s_waitcnt lgkmcnt(2)
	v_mfma_f32_32x32x16_bf16 v[114:129], v[178:181], v[194:197], v[114:129]
	v_mfma_f32_32x32x16_bf16 v[50:65], v[182:185], v[194:197], v[50:65]
	ds_read_b128 v[194:197], v235 offset:28672
	ds_read_b128 v[186:189], v226
	s_and_b64 exec, vcc, s[4:5]
	global_load_dwordx4 v[134:137], v202, s[26:27]
	s_mov_b64 exec, vcc
	s_waitcnt lgkmcnt(3)
	v_mfma_f32_32x32x16_bf16 v[98:113], v[178:181], v[198:201], v[98:113]
	v_mfma_f32_32x32x16_bf16 v[34:49], v[182:185], v[198:201], v[34:49]
	ds_read_b128 v[198:201], v236 offset:16384
	ds_read_b128 v[190:193], v226 offset:4096
	s_and_b64 exec, vcc, s[6:7]
	global_load_dwordx4 v[130:133], v203, s[26:27]
	s_mov_b64 exec, vcc
	s_waitcnt lgkmcnt(4)
	v_mfma_f32_32x32x16_bf16 v[82:97], v[178:181], v[210:213], v[82:97]
	v_mfma_f32_32x32x16_bf16 v[18:33], v[182:185], v[210:213], v[18:33]
	ds_read_b128 v[210:213], v236 offset:20480
	s_and_b64 exec, vcc, s[8:9]
	global_load_dwordx4 v[142:145], v230, s[26:27]
	s_mov_b64 exec, vcc
	s_waitcnt lgkmcnt(4)
	v_mfma_f32_32x32x16_bf16 v[66:81], v[178:181], v[194:197], v[66:81]
	v_mfma_f32_32x32x16_bf16 v[2:17], v[182:185], v[194:197], v[2:17]
	ds_read_b128 v[194:197], v236 offset:24576
	s_and_b64 exec, vcc, s[10:11]
	global_load_dwordx4 v[138:141], v231, s[26:27]
	s_mov_b64 exec, vcc
	s_add_u32 s26, s26, 0x80
	s_addc_u32 s27, s27, 0
	s_waitcnt lgkmcnt(2)
	v_mfma_f32_32x32x16_bf16 v[114:129], v[186:189], v[198:201], v[114:129]
	v_mfma_f32_32x32x16_bf16 v[50:65], v[190:193], v[198:201], v[50:65]
	ds_read_b128 v[198:201], v236 offset:28672
	ds_read_b128 v[178:181], v228
	global_load_dwordx4 v[146:149], v232, s[100:101]
	s_waitcnt lgkmcnt(3)
	v_mfma_f32_32x32x16_bf16 v[98:113], v[186:189], v[210:213], v[98:113]
	v_mfma_f32_32x32x16_bf16 v[34:49], v[190:193], v[210:213], v[34:49]
	ds_read_b128 v[210:213], v237 offset:16384
	ds_read_b128 v[182:185], v228 offset:4096
	v_add_u32_e32 v233, 0x20000, v232
	global_load_dwordx4 v[150:153], v233, s[100:101]
	s_waitcnt lgkmcnt(4)
	v_mfma_f32_32x32x16_bf16 v[82:97], v[186:189], v[194:197], v[82:97]
	v_mfma_f32_32x32x16_bf16 v[18:33], v[190:193], v[194:197], v[18:33]
	ds_read_b128 v[194:197], v237 offset:20480
	v_add_u32_e32 v234, 0x40000, v232
	global_load_dwordx4 v[154:157], v234, s[100:101]
	s_waitcnt lgkmcnt(4)
	v_mfma_f32_32x32x16_bf16 v[66:81], v[186:189], v[198:201], v[66:81]
	v_mfma_f32_32x32x16_bf16 v[2:17], v[190:193], v[198:201], v[2:17]
	ds_read_b128 v[198:201], v237 offset:24576
	v_add_u32_e32 v233, 0x60000, v232
	global_load_dwordx4 v[158:161], v233, s[100:101]
	s_waitcnt lgkmcnt(2)
	v_mfma_f32_32x32x16_bf16 v[114:129], v[178:181], v[210:213], v[114:129]
	v_mfma_f32_32x32x16_bf16 v[50:65], v[182:185], v[210:213], v[50:65]
	ds_read_b128 v[210:213], v237 offset:28672
	ds_read_b128 v[186:189], v229
	v_add_u32_e32 v234, 0x80000, v232
	global_load_dwordx4 v[162:165], v234, s[100:101]
	s_waitcnt lgkmcnt(3)
	v_mfma_f32_32x32x16_bf16 v[98:113], v[178:181], v[194:197], v[98:113]
	v_mfma_f32_32x32x16_bf16 v[34:49], v[182:185], v[194:197], v[34:49]
	ds_read_b128 v[194:197], v238 offset:16384
	ds_read_b128 v[190:193], v229 offset:4096
	v_add_u32_e32 v233, 0xa0000, v232
	global_load_dwordx4 v[166:169], v233, s[100:101]
	s_waitcnt lgkmcnt(4)
	v_mfma_f32_32x32x16_bf16 v[82:97], v[178:181], v[198:201], v[82:97]
	v_mfma_f32_32x32x16_bf16 v[18:33], v[182:185], v[198:201], v[18:33]
	ds_read_b128 v[198:201], v238 offset:20480
	v_add_u32_e32 v234, 0xc0000, v232
	global_load_dwordx4 v[170:173], v234, s[100:101]
	s_waitcnt lgkmcnt(4)
	v_mfma_f32_32x32x16_bf16 v[66:81], v[178:181], v[210:213], v[66:81]
	v_mfma_f32_32x32x16_bf16 v[2:17], v[182:185], v[210:213], v[2:17]
	ds_read_b128 v[210:213], v238 offset:24576
	v_add_u32_e32 v233, 0xe0000, v232
	global_load_dwordx4 v[174:177], v233, s[100:101]
	s_add_u32 s100, s100, 0x80
	s_addc_u32 s101, s101, 0
	s_waitcnt lgkmcnt(2)
	v_mfma_f32_32x32x16_bf16 v[114:129], v[186:189], v[194:197], v[114:129]
	v_mfma_f32_32x32x16_bf16 v[50:65], v[190:193], v[194:197], v[50:65]
	ds_read_b128 v[194:197], v238 offset:28672
	s_waitcnt lgkmcnt(2)
	v_mfma_f32_32x32x16_bf16 v[98:113], v[186:189], v[198:201], v[98:113]
	v_mfma_f32_32x32x16_bf16 v[34:49], v[190:193], v[198:201], v[34:49]
	s_waitcnt lgkmcnt(1)
	v_mfma_f32_32x32x16_bf16 v[82:97], v[186:189], v[210:213], v[82:97]
	v_mfma_f32_32x32x16_bf16 v[18:33], v[190:193], v[210:213], v[18:33]
	s_waitcnt lgkmcnt(0)
	v_mfma_f32_32x32x16_bf16 v[66:81], v[186:189], v[194:197], v[66:81]
	v_mfma_f32_32x32x16_bf16 v[2:17], v[190:193], v[194:197], v[2:17]
	s_setprio 0
	s_barrier
	s_branch .Lg3_head

.LBB0_1966:
	s_waitcnt vmcnt(8)
	v_add_u32_e32 v130, s20, v204
	v_ashrrev_i32_e32 v131, 31, v130
	s_and_b32 s100, s38, 7
	s_lshl_b32 s100, s100, 6
	s_bfe_u32 s101, s38, 0x60003
	s_or_b32 s100, s100, s101
	s_and_b32 s101, s38, 0x200
	s_or_b32 s100, s100, s101
	s_lshr_b32 s5, s100, 9
	s_and_b32 s4, s40, 7
	v_lshlrev_b64 v[132:133], 13, v[130:131]
	s_mul_i32 s8, s5, 0x1800
	v_lshl_add_u64 v[130:131], s[12:13], 0, v[132:133]
	v_lshl_add_u64 v[132:133], s[16:17], 0, v[132:133]
	s_addk_i32 s8, 0x1000
	v_or_b32_e32 v142, s39, v1
	v_lshl_or_b32 v143, s4, 8, v1
	s_mov_b32 s9, 0
	s_mov_b64 s[6:7], -1

.Lg4_head:
	s_cmpk_gt_u32 s39, 0x7bf
	s_waitcnt vmcnt(0)
	ds_write_b128 v224, v[134:137]
	ds_write_b128 v224, v[130:133] offset:4096
	ds_write_b128 v224, v[142:145] offset:8192
	ds_write_b128 v224, v[138:141] offset:12288
	ds_write_b128 v224, v[146:149] offset:16384
	ds_write_b128 v224, v[150:153] offset:20480
	ds_write_b128 v224, v[154:157] offset:24576
	ds_write_b128 v224, v[158:161] offset:28672
	ds_write_b128 v224, v[162:165] offset:32768
	ds_write_b128 v224, v[166:169] offset:36864
	ds_write_b128 v224, v[170:173] offset:40960
	ds_write_b128 v224, v[174:177] offset:45056
	s_waitcnt lgkmcnt(0)
	s_barrier
	s_cbranch_scc1 .Lg4_final
	s_add_i32 s39, s39, 64
	ds_read_b128 v[180:183], v226
	ds_read_b128 v[184:187], v226 offset:4096
	ds_read_b128 v[196:199], v237 offset:16384
	ds_read_b128 v[200:203], v237 offset:20480
	ds_read_b128 v[210:213], v237 offset:24576
	s_setprio 1
	s_waitcnt lgkmcnt(2)
	v_mfma_f32_32x32x16_bf16 v[114:129], v[180:183], v[196:199], v[114:129]
	v_mfma_f32_32x32x16_bf16 v[50:65], v[184:187], v[196:199], v[50:65]
	ds_read_b128 v[196:199], v237 offset:28672
	ds_read_b128 v[188:191], v228
	s_and_b64 exec, vcc, s[14:15]
	global_load_dwordx4 v[134:137], v204, s[22:23]
	s_mov_b64 exec, vcc
	s_waitcnt lgkmcnt(3)
	v_mfma_f32_32x32x16_bf16 v[98:113], v[180:183], v[200:203], v[98:113]
	v_mfma_f32_32x32x16_bf16 v[34:49], v[184:187], v[200:203], v[34:49]
	ds_read_b128 v[200:203], v238 offset:16384
	ds_read_b128 v[192:195], v228 offset:4096
	s_and_b64 exec, vcc, s[16:17]
	global_load_dwordx4 v[130:133], v205, s[22:23]
	s_mov_b64 exec, vcc
	s_waitcnt lgkmcnt(4)
	v_mfma_f32_32x32x16_bf16 v[82:97], v[180:183], v[210:213], v[82:97]
	v_mfma_f32_32x32x16_bf16 v[18:33], v[184:187], v[210:213], v[18:33]
	ds_read_b128 v[210:213], v238 offset:20480
	s_and_b64 exec, vcc, s[18:19]
	global_load_dwordx4 v[142:145], v232, s[22:23]
	s_mov_b64 exec, vcc
	s_waitcnt lgkmcnt(4)
	v_mfma_f32_32x32x16_bf16 v[66:81], v[180:183], v[196:199], v[66:81]
	v_mfma_f32_32x32x16_bf16 v[2:17], v[184:187], v[196:199], v[2:17]
	ds_read_b128 v[196:199], v238 offset:24576
	s_and_b64 exec, vcc, s[4:5]
	global_load_dwordx4 v[138:141], v233, s[22:23]
	s_mov_b64 exec, vcc
	s_add_u32 s22, s22, 0x80
	s_addc_u32 s23, s23, 0
	s_waitcnt lgkmcnt(2)
	v_mfma_f32_32x32x16_bf16 v[114:129], v[188:191], v[200:203], v[114:129]
	v_mfma_f32_32x32x16_bf16 v[50:65], v[192:195], v[200:203], v[50:65]
	ds_read_b128 v[200:203], v238 offset:28672
	ds_read_b128 v[180:183], v230
	global_load_dwordx4 v[146:149], v234, s[100:101]
	s_waitcnt lgkmcnt(3)
	v_mfma_f32_32x32x16_bf16 v[98:113], v[188:191], v[210:213], v[98:113]
	v_mfma_f32_32x32x16_bf16 v[34:49], v[192:195], v[210:213], v[34:49]
	ds_read_b128 v[210:213], v239 offset:16384
	ds_read_b128 v[184:187], v230 offset:4096
	v_add_u32_e32 v235, 0x20000, v234
	global_load_dwordx4 v[150:153], v235, s[100:101]
	s_waitcnt lgkmcnt(4)
	v_mfma_f32_32x32x16_bf16 v[82:97], v[188:191], v[196:199], v[82:97]
	v_mfma_f32_32x32x16_bf16 v[18:33], v[192:195], v[196:199], v[18:33]
	ds_read_b128 v[196:199], v239 offset:20480
	v_add_u32_e32 v236, 0x40000, v234
	global_load_dwordx4 v[154:157], v236, s[100:101]
	s_waitcnt lgkmcnt(4)
	v_mfma_f32_32x32x16_bf16 v[66:81], v[188:191], v[200:203], v[66:81]
	v_mfma_f32_32x32x16_bf16 v[2:17], v[192:195], v[200:203], v[2:17]
	ds_read_b128 v[200:203], v239 offset:24576
	v_add_u32_e32 v235, 0x60000, v234
	global_load_dwordx4 v[158:161], v235, s[100:101]
	s_waitcnt lgkmcnt(2)
	v_mfma_f32_32x32x16_bf16 v[114:129], v[180:183], v[210:213], v[114:129]
	v_mfma_f32_32x32x16_bf16 v[50:65], v[184:187], v[210:213], v[50:65]
	ds_read_b128 v[210:213], v239 offset:28672
	ds_read_b128 v[188:191], v231
	v_add_u32_e32 v236, 0x80000, v234
	global_load_dwordx4 v[162:165], v236, s[100:101]
	s_waitcnt lgkmcnt(3)
	v_mfma_f32_32x32x16_bf16 v[98:113], v[180:183], v[196:199], v[98:113]
	v_mfma_f32_32x32x16_bf16 v[34:49], v[184:187], v[196:199], v[34:49]
	ds_read_b128 v[196:199], v240 offset:16384
	ds_read_b128 v[192:195], v231 offset:4096
	v_add_u32_e32 v235, 0xa0000, v234
	global_load_dwordx4 v[166:169], v235, s[100:101]
	s_waitcnt lgkmcnt(4)
	v_mfma_f32_32x32x16_bf16 v[82:97], v[180:183], v[200:203], v[82:97]
	v_mfma_f32_32x32x16_bf16 v[18:33], v[184:187], v[200:203], v[18:33]
	ds_read_b128 v[200:203], v240 offset:20480
	v_add_u32_e32 v236, 0xc0000, v234
	global_load_dwordx4 v[170:173], v236, s[100:101]
	s_waitcnt lgkmcnt(4)
	v_mfma_f32_32x32x16_bf16 v[66:81], v[180:183], v[210:213], v[66:81]
	v_mfma_f32_32x32x16_bf16 v[2:17], v[184:187], v[210:213], v[2:17]
	ds_read_b128 v[210:213], v240 offset:24576
	v_add_u32_e32 v235, 0xe0000, v234
	global_load_dwordx4 v[174:177], v235, s[100:101]
	s_add_u32 s100, s100, 0x80
	s_addc_u32 s101, s101, 0
	s_waitcnt lgkmcnt(2)
	v_mfma_f32_32x32x16_bf16 v[114:129], v[188:191], v[196:199], v[114:129]
	v_mfma_f32_32x32x16_bf16 v[50:65], v[192:195], v[196:199], v[50:65]
	ds_read_b128 v[196:199], v240 offset:28672
	s_waitcnt lgkmcnt(2)
	v_mfma_f32_32x32x16_bf16 v[98:113], v[188:191], v[200:203], v[98:113]
	v_mfma_f32_32x32x16_bf16 v[34:49], v[192:195], v[200:203], v[34:49]
	s_waitcnt lgkmcnt(1)
	v_mfma_f32_32x32x16_bf16 v[82:97], v[188:191], v[210:213], v[82:97]
	v_mfma_f32_32x32x16_bf16 v[18:33], v[192:195], v[210:213], v[18:33]
	s_waitcnt lgkmcnt(0)
	v_mfma_f32_32x32x16_bf16 v[66:81], v[188:191], v[196:199], v[66:81]
	v_mfma_f32_32x32x16_bf16 v[2:17], v[192:195], v[196:199], v[2:17]
	s_setprio 0
	s_barrier
	s_branch .Lg4_head

.LBB0_2166:
	v_mov_b32_e32 v14, v208
	s_and_b32 s100, s29, 7
	s_lshl_b32 s100, s100, 6
	s_bfe_u32 s101, s29, 0x60003
	s_or_b32 s100, s100, s101
	s_and_b32 s101, s29, 0x200
	s_or_b32 s100, s100, s101
	s_lshl_b32 s2, s100, 4
	v_lshlrev_b32_e32 v15, 3, v14
	v_and_b32_e32 v2, 56, v15
	s_and_b32 s16, s2, 0xffffff80
	v_lshlrev_b32_e32 v8, 1, v2
	v_ashrrev_i32_e32 v2, 3, v14
	v_mov_b32_e32 v9, v0
	v_add_u32_e32 v3, s16, v2
	v_lshl_add_u64 v[12:13], s[10:11], 0, v[8:9]
	v_cmp_gt_u32_e64 s[2:3], s50, v3
	v_mov_b32_e32 v130, 0
	v_mov_b32_e32 v134, 0
	v_mov_b32_e32 v135, 0
	v_mov_b32_e32 v136, 0
	v_mov_b32_e32 v137, 0
	s_and_saveexec_b64 s[4:5], s[2:3]
	s_cbranch_execz .LBB0_2168
	v_lshlrev_b32_e32 v4, 13, v3
	v_mov_b32_e32 v5, v0
	v_lshl_add_u64 v[4:5], v[12:13], 0, v[4:5]
	global_load_dwordx4 v[134:137], v[4:5], off

.LBB0_2174:
	s_or_b64 exec, exec, s[16:17]
	s_and_b32 s100, s29, 7
	s_lshl_b32 s100, s100, 6
	s_bfe_u32 s101, s29, 0x60003
	s_or_b32 s100, s100, s101
	s_and_b32 s101, s29, 0x200
	s_or_b32 s100, s100, s101
	s_lshl_b32 s18, s100, 8
	s_lshl_b32 s16, s100, 4
	s_and_b32 s16, s16, 0xffffff80
	s_lshl_b32 s17, s100, 21
	s_and_b32 s31, s18, 0x700
	s_mov_b32 s30, s100
	s_and_b32 s20, s17, 0xe00000
	s_ashr_i32 s17, s16, 31
	s_lshl_b32 s18, s31, 13
	s_add_u32 s18, s22, s18
	s_addc_u32 s19, s23, 0
	v_mov_b32_e32 v9, v0
	v_ashrrev_i32_e32 v3, 31, v2
	v_lshl_add_u64 v[8:9], s[18:19], 0, v[8:9]
	v_lshlrev_b64 v[12:13], 13, v[2:3]
	v_ashrrev_i32_e32 v5, 31, v4
	v_lshl_add_u64 v[16:17], v[8:9], 0, v[12:13]
	v_lshlrev_b64 v[18:19], 13, v[4:5]
	v_ashrrev_i32_e32 v7, 31, v6
	v_lshl_add_u64 v[20:21], v[8:9], 0, v[18:19]
	global_load_dwordx4 v[146:149], v[16:17], off
	global_load_dwordx4 v[150:153], v[20:21], off
	v_lshlrev_b64 v[16:17], 13, v[6:7]
	v_ashrrev_i32_e32 v11, 31, v10
	v_lshl_add_u64 v[20:21], v[8:9], 0, v[16:17]
	v_lshlrev_b64 v[22:23], 13, v[10:11]
	v_lshl_add_u64 v[24:25], v[8:9], 0, v[22:23]
	global_load_dwordx4 v[154:157], v[20:21], off
	global_load_dwordx4 v[158:161], v[24:25], off
	v_add_u32_e32 v20, 0x400, v14
	v_ashrrev_i32_e32 v20, 3, v20
	v_add_u32_e32 v26, 0x500, v14
	v_ashrrev_i32_e32 v21, 31, v20
	v_ashrrev_i32_e32 v26, 3, v26
	v_lshlrev_b64 v[20:21], 13, v[20:21]
	v_ashrrev_i32_e32 v27, 31, v26
	v_lshl_add_u64 v[24:25], v[8:9], 0, v[20:21]
	v_lshlrev_b64 v[26:27], 13, v[26:27]
	v_lshl_add_u64 v[28:29], v[8:9], 0, v[26:27]
	global_load_dwordx4 v[162:165], v[24:25], off
	global_load_dwordx4 v[166:169], v[28:29], off
	v_add_u32_e32 v24, 0x600, v14
	v_ashrrev_i32_e32 v24, 3, v24
	v_add_u32_e32 v30, 0x700, v14
	v_ashrrev_i32_e32 v25, 31, v24
	v_ashrrev_i32_e32 v30, 3, v30
	v_lshlrev_b64 v[24:25], 13, v[24:25]
	v_ashrrev_i32_e32 v31, 31, v30
	v_lshl_add_u64 v[28:29], v[8:9], 0, v[24:25]
	v_lshlrev_b64 v[30:31], 13, v[30:31]
	v_lshl_add_u64 v[8:9], v[8:9], 0, v[30:31]
	global_load_dwordx4 v[170:173], v[28:29], off
	global_load_dwordx4 v[174:177], v[8:9], off
	v_lshrrev_b32_e32 v9, 4, v14
	v_xor_b32_e32 v9, v9, v14
	v_and_b32_e32 v15, 0x7fffffc0, v15
	v_lshrrev_b32_e32 v33, 5, v14
	v_lshlrev_b32_e32 v9, 4, v9
	v_bfe_u32 v29, v14, 1, 3
	v_lshlrev_b32_e32 v15, 1, v15
	v_and_b32_e32 v32, 31, v14
	v_bfe_u32 v8, v14, 5, 1
	v_lshrrev_b32_e32 v28, 1, v14
	v_lshlrev_b32_e32 v34, 1, v14
	v_and_or_b32 v222, v9, s45, v15
	v_bitop3_b32 v9, v33, v29, 1 bitop3:0x6c
	v_and_or_b32 v28, v28, s87, v32
	v_and_or_b32 v32, v34, s35, v32
	v_bitop3_b32 v34, v8, v29, 6 bitop3:0x36
	v_lshlrev_b32_e32 v223, 4, v9
	v_bitop3_b32 v9, v8, v29, 2 bitop3:0x36
	v_bitop3_b32 v8, v8, v29, 4 bitop3:0x36
	v_lshlrev_b32_e32 v227, 4, v8
	v_and_b32_e32 v8, 7, v14
	v_lshl_add_u64 v[2:3], v[2:3], 0, s[16:17]
	v_lshlrev_b32_e32 v225, 4, v9
	v_lshlrev_b32_e32 v178, 4, v8
	s_add_u32 s18, s24, s20
	v_lshl_add_u64 v[8:9], v[10:11], 0, s[16:17]
	v_lshl_add_u64 v[6:7], v[6:7], 0, s[16:17]
	v_lshl_add_u64 v[4:5], v[4:5], 0, s[16:17]
	v_lshlrev_b64 v[2:3], 13, v[2:3]
	v_lshlrev_b32_e32 v28, 7, v28
	v_lshlrev_b32_e32 v206, 4, v34
	s_addc_u32 s19, s26, 0
	v_lshlrev_b64 v[8:9], 13, v[8:9]
	v_lshlrev_b64 v[6:7], 13, v[6:7]
	v_lshlrev_b64 v[4:5], 13, v[4:5]
	v_lshl_add_u64 v[202:203], s[12:13], 0, v[2:3]
	v_mov_b32_e32 v2, 0
	v_lshlrev_b32_e32 v207, 7, v32
	v_or_b32_e32 v224, v28, v223
	v_or_b32_e32 v226, v28, v225
	v_or_b32_e32 v228, v28, v227
	v_or_b32_e32 v229, v28, v206
	v_mov_b32_e32 v179, v0
	v_lshl_add_u64 v[180:181], s[18:19], 0, v[30:31]
	v_lshl_add_u64 v[182:183], s[18:19], 0, v[24:25]
	v_lshl_add_u64 v[184:185], s[18:19], 0, v[26:27]
	v_lshl_add_u64 v[186:187], s[18:19], 0, v[20:21]
	v_lshl_add_u64 v[188:189], s[18:19], 0, v[22:23]
	v_lshl_add_u64 v[190:191], s[18:19], 0, v[16:17]
	v_lshl_add_u64 v[192:193], s[18:19], 0, v[18:19]
	v_lshl_add_u64 v[194:195], s[18:19], 0, v[12:13]
	v_lshl_add_u64 v[196:197], s[12:13], 0, v[8:9]
	v_lshl_add_u64 v[198:199], s[12:13], 0, v[6:7]
	v_lshl_add_u64 v[200:201], s[12:13], 0, v[4:5]
	s_mov_b32 s17, 0
	v_mov_b32_e32 v3, v2
	v_mov_b32_e32 v4, v2
	v_mov_b32_e32 v5, v2
	v_mov_b32_e32 v6, v2
	v_mov_b32_e32 v7, v2
	v_mov_b32_e32 v8, v2
	v_mov_b32_e32 v9, v2
	v_mov_b32_e32 v10, v2
	v_mov_b32_e32 v11, v2
	v_mov_b32_e32 v12, v2
	v_mov_b32_e32 v13, v2
	v_mov_b32_e32 v14, v2
	v_mov_b32_e32 v15, v2
	v_mov_b32_e32 v16, v2
	v_mov_b32_e32 v17, v2
	v_mov_b32_e32 v18, v2
	v_mov_b32_e32 v19, v2
	v_mov_b32_e32 v20, v2
	v_mov_b32_e32 v21, v2
	v_mov_b32_e32 v22, v2
	v_mov_b32_e32 v23, v2
	v_mov_b32_e32 v24, v2
	v_mov_b32_e32 v25, v2
	v_mov_b32_e32 v26, v2
	v_mov_b32_e32 v27, v2
	v_mov_b32_e32 v28, v2
	v_mov_b32_e32 v29, v2
	v_mov_b32_e32 v30, v2
	v_mov_b32_e32 v31, v2
	v_mov_b32_e32 v32, v2
	v_mov_b32_e32 v33, v2
	v_mov_b32_e32 v34, v2
	v_mov_b32_e32 v35, v2
	v_mov_b32_e32 v36, v2
	v_mov_b32_e32 v37, v2
	v_mov_b32_e32 v38, v2
	v_mov_b32_e32 v39, v2
	v_mov_b32_e32 v40, v2
	v_mov_b32_e32 v41, v2
	v_mov_b32_e32 v42, v2
	v_mov_b32_e32 v43, v2
	v_mov_b32_e32 v44, v2
	v_mov_b32_e32 v45, v2
	v_mov_b32_e32 v46, v2
	v_mov_b32_e32 v47, v2
	v_mov_b32_e32 v48, v2
	v_mov_b32_e32 v49, v2
	v_mov_b32_e32 v50, v2
	v_mov_b32_e32 v51, v2
	v_mov_b32_e32 v52, v2
	v_mov_b32_e32 v53, v2
	v_mov_b32_e32 v54, v2
	v_mov_b32_e32 v55, v2
	v_mov_b32_e32 v56, v2
	v_mov_b32_e32 v57, v2
	v_mov_b32_e32 v58, v2
	v_mov_b32_e32 v59, v2
	v_mov_b32_e32 v60, v2
	v_mov_b32_e32 v61, v2
	v_mov_b32_e32 v62, v2
	v_mov_b32_e32 v63, v2
	v_mov_b32_e32 v64, v2
	v_mov_b32_e32 v65, v2
	v_mov_b32_e32 v66, v2
	v_mov_b32_e32 v67, v2
	v_mov_b32_e32 v68, v2
	v_mov_b32_e32 v69, v2
	v_mov_b32_e32 v70, v2
	v_mov_b32_e32 v71, v2
	v_mov_b32_e32 v72, v2
	v_mov_b32_e32 v73, v2
	v_mov_b32_e32 v74, v2
	v_mov_b32_e32 v75, v2
	v_mov_b32_e32 v76, v2
	v_mov_b32_e32 v77, v2
	v_mov_b32_e32 v78, v2
	v_mov_b32_e32 v79, v2
	v_mov_b32_e32 v80, v2
	v_mov_b32_e32 v81, v2
	v_mov_b32_e32 v82, v2
	v_mov_b32_e32 v83, v2
	v_mov_b32_e32 v84, v2
	v_mov_b32_e32 v85, v2
	v_mov_b32_e32 v86, v2
	v_mov_b32_e32 v87, v2
	v_mov_b32_e32 v88, v2
	v_mov_b32_e32 v89, v2
	v_mov_b32_e32 v90, v2
	v_mov_b32_e32 v91, v2
	v_mov_b32_e32 v92, v2
	v_mov_b32_e32 v93, v2
	v_mov_b32_e32 v94, v2
	v_mov_b32_e32 v95, v2
	v_mov_b32_e32 v96, v2
	v_mov_b32_e32 v97, v2
	v_mov_b32_e32 v98, v2
	v_mov_b32_e32 v99, v2
	v_mov_b32_e32 v100, v2
	v_mov_b32_e32 v101, v2
	v_mov_b32_e32 v102, v2
	v_mov_b32_e32 v103, v2
	v_mov_b32_e32 v104, v2
	v_mov_b32_e32 v105, v2
	v_mov_b32_e32 v106, v2
	v_mov_b32_e32 v107, v2
	v_mov_b32_e32 v108, v2
	v_mov_b32_e32 v109, v2
	v_mov_b32_e32 v110, v2
	v_mov_b32_e32 v111, v2
	v_mov_b32_e32 v112, v2
	v_mov_b32_e32 v113, v2
	v_mov_b32_e32 v114, v2
	v_mov_b32_e32 v115, v2
	v_mov_b32_e32 v116, v2
	v_mov_b32_e32 v117, v2
	v_mov_b32_e32 v118, v2
	v_mov_b32_e32 v119, v2
	v_mov_b32_e32 v120, v2
	v_mov_b32_e32 v121, v2
	v_mov_b32_e32 v122, v2
	v_mov_b32_e32 v123, v2
	v_mov_b32_e32 v124, v2
	v_mov_b32_e32 v125, v2
	v_mov_b32_e32 v126, v2
	v_mov_b32_e32 v127, v2
	v_mov_b32_e32 v128, v2
	v_mov_b32_e32 v129, v2
	s_branch .Lg5_pre

.Lg5_head:
	s_cmpk_gt_u32 s17, 0xfbf
	s_waitcnt vmcnt(0)
	ds_write_b128 v222, v[134:137]
	ds_write_b128 v222, v[130:133] offset:4096
	ds_write_b128 v222, v[142:145] offset:8192
	ds_write_b128 v222, v[138:141] offset:12288
	ds_write_b128 v222, v[146:149] offset:16384
	ds_write_b128 v222, v[150:153] offset:20480
	ds_write_b128 v222, v[154:157] offset:24576
	ds_write_b128 v222, v[158:161] offset:28672
	ds_write_b128 v222, v[162:165] offset:32768
	ds_write_b128 v222, v[166:169] offset:36864
	ds_write_b128 v222, v[170:173] offset:40960
	ds_write_b128 v222, v[174:177] offset:45056
	s_waitcnt lgkmcnt(0)
	s_barrier
	s_cbranch_scc1 .Lg5_final
	s_add_i32 s17, s17, 64
	ds_read_b128 v[178:181], v224
	ds_read_b128 v[182:185], v224 offset:4096
	ds_read_b128 v[194:197], v235 offset:16384
	ds_read_b128 v[198:201], v235 offset:20480
	ds_read_b128 v[210:213], v235 offset:24576
	s_setprio 1
	s_waitcnt lgkmcnt(2)
	v_mfma_f32_32x32x16_bf16 v[114:129], v[178:181], v[194:197], v[114:129]
	v_mfma_f32_32x32x16_bf16 v[50:65], v[182:185], v[194:197], v[50:65]
	ds_read_b128 v[194:197], v235 offset:28672
	ds_read_b128 v[186:189], v226
	s_and_b64 exec, vcc, s[2:3]
	global_load_dwordx4 v[134:137], v202, s[20:21]
	s_mov_b64 exec, vcc
	s_waitcnt lgkmcnt(3)
	v_mfma_f32_32x32x16_bf16 v[98:113], v[178:181], v[198:201], v[98:113]
	v_mfma_f32_32x32x16_bf16 v[34:49], v[182:185], v[198:201], v[34:49]
	ds_read_b128 v[198:201], v236 offset:16384
	ds_read_b128 v[190:193], v226 offset:4096
	s_and_b64 exec, vcc, s[4:5]
	global_load_dwordx4 v[130:133], v203, s[20:21]
	s_mov_b64 exec, vcc
	s_waitcnt lgkmcnt(4)
	v_mfma_f32_32x32x16_bf16 v[82:97], v[178:181], v[210:213], v[82:97]
	v_mfma_f32_32x32x16_bf16 v[18:33], v[182:185], v[210:213], v[18:33]
	ds_read_b128 v[210:213], v236 offset:20480
	s_and_b64 exec, vcc, s[6:7]
	global_load_dwordx4 v[142:145], v230, s[20:21]
	s_mov_b64 exec, vcc
	s_waitcnt lgkmcnt(4)
	v_mfma_f32_32x32x16_bf16 v[66:81], v[178:181], v[194:197], v[66:81]
	v_mfma_f32_32x32x16_bf16 v[2:17], v[182:185], v[194:197], v[2:17]
	ds_read_b128 v[194:197], v236 offset:24576
	s_and_b64 exec, vcc, s[8:9]
	global_load_dwordx4 v[138:141], v231, s[20:21]
	s_mov_b64 exec, vcc
	s_add_u32 s20, s20, 0x80
	s_addc_u32 s21, s21, 0
	s_waitcnt lgkmcnt(2)
	v_mfma_f32_32x32x16_bf16 v[114:129], v[186:189], v[198:201], v[114:129]
	v_mfma_f32_32x32x16_bf16 v[50:65], v[190:193], v[198:201], v[50:65]
	ds_read_b128 v[198:201], v236 offset:28672
	ds_read_b128 v[178:181], v228
	global_load_dwordx4 v[146:149], v232, s[100:101]
	s_waitcnt lgkmcnt(3)
	v_mfma_f32_32x32x16_bf16 v[98:113], v[186:189], v[210:213], v[98:113]
	v_mfma_f32_32x32x16_bf16 v[34:49], v[190:193], v[210:213], v[34:49]
	ds_read_b128 v[210:213], v237 offset:16384
	ds_read_b128 v[182:185], v228 offset:4096
	v_add_u32_e32 v233, 0x40000, v232
	global_load_dwordx4 v[150:153], v233, s[100:101]
	s_waitcnt lgkmcnt(4)
	v_mfma_f32_32x32x16_bf16 v[82:97], v[186:189], v[194:197], v[82:97]
	v_mfma_f32_32x32x16_bf16 v[18:33], v[190:193], v[194:197], v[18:33]
	ds_read_b128 v[194:197], v237 offset:20480
	v_add_u32_e32 v234, 0x80000, v232
	global_load_dwordx4 v[154:157], v234, s[100:101]
	s_waitcnt lgkmcnt(4)
	v_mfma_f32_32x32x16_bf16 v[66:81], v[186:189], v[198:201], v[66:81]
	v_mfma_f32_32x32x16_bf16 v[2:17], v[190:193], v[198:201], v[2:17]
	ds_read_b128 v[198:201], v237 offset:24576
	v_add_u32_e32 v233, 0xc0000, v232
	global_load_dwordx4 v[158:161], v233, s[100:101]
	s_waitcnt lgkmcnt(2)
	v_mfma_f32_32x32x16_bf16 v[114:129], v[178:181], v[210:213], v[114:129]
	v_mfma_f32_32x32x16_bf16 v[50:65], v[182:185], v[210:213], v[50:65]
	ds_read_b128 v[210:213], v237 offset:28672
	ds_read_b128 v[186:189], v229
	v_add_u32_e32 v234, 0x100000, v232
	global_load_dwordx4 v[162:165], v234, s[100:101]
	s_waitcnt lgkmcnt(3)
	v_mfma_f32_32x32x16_bf16 v[98:113], v[178:181], v[194:197], v[98:113]
	v_mfma_f32_32x32x16_bf16 v[34:49], v[182:185], v[194:197], v[34:49]
	ds_read_b128 v[194:197], v238 offset:16384
	ds_read_b128 v[190:193], v229 offset:4096
	v_add_u32_e32 v233, 0x140000, v232
	global_load_dwordx4 v[166:169], v233, s[100:101]
	s_waitcnt lgkmcnt(4)
	v_mfma_f32_32x32x16_bf16 v[82:97], v[178:181], v[198:201], v[82:97]
	v_mfma_f32_32x32x16_bf16 v[18:33], v[182:185], v[198:201], v[18:33]
	ds_read_b128 v[198:201], v238 offset:20480
	v_add_u32_e32 v234, 0x180000, v232
	global_load_dwordx4 v[170:173], v234, s[100:101]
	s_waitcnt lgkmcnt(4)
	v_mfma_f32_32x32x16_bf16 v[66:81], v[178:181], v[210:213], v[66:81]
	v_mfma_f32_32x32x16_bf16 v[2:17], v[182:185], v[210:213], v[2:17]
	ds_read_b128 v[210:213], v238 offset:24576
	v_add_u32_e32 v233, 0x1c0000, v232
	global_load_dwordx4 v[174:177], v233, s[100:101]
	s_add_u32 s100, s100, 0x80
	s_addc_u32 s101, s101, 0
	s_waitcnt lgkmcnt(2)
	v_mfma_f32_32x32x16_bf16 v[114:129], v[186:189], v[194:197], v[114:129]
	v_mfma_f32_32x32x16_bf16 v[50:65], v[190:193], v[194:197], v[50:65]
	ds_read_b128 v[194:197], v238 offset:28672
	s_waitcnt lgkmcnt(2)
	v_mfma_f32_32x32x16_bf16 v[98:113], v[186:189], v[198:201], v[98:113]
	v_mfma_f32_32x32x16_bf16 v[34:49], v[190:193], v[198:201], v[34:49]
	s_waitcnt lgkmcnt(1)
	v_mfma_f32_32x32x16_bf16 v[82:97], v[186:189], v[210:213], v[82:97]
	v_mfma_f32_32x32x16_bf16 v[18:33], v[190:193], v[210:213], v[18:33]
	s_waitcnt lgkmcnt(0)
	v_mfma_f32_32x32x16_bf16 v[66:81], v[186:189], v[194:197], v[66:81]
	v_mfma_f32_32x32x16_bf16 v[2:17], v[190:193], v[194:197], v[2:17]
	s_setprio 0
	s_barrier
	s_branch .Lg5_head

.LBB0_2186:
	s_waitcnt vmcnt(8)
	v_add_u32_e32 v130, s16, v204
	v_ashrrev_i32_e32 v131, 31, v130
	s_and_b32 s100, s29, 7
	s_lshl_b32 s100, s100, 6
	s_bfe_u32 s101, s29, 0x60003
	s_or_b32 s100, s100, s101
	s_and_b32 s101, s29, 0x200
	s_or_b32 s100, s100, s101
	s_lshr_b32 s3, s100, 9
	v_lshlrev_b64 v[130:131], 13, v[130:131]
	s_and_b32 s2, s30, 7
	s_mul_i32 s6, s3, 0x1800
	s_addk_i32 s6, 0x1000
	s_waitcnt vmcnt(3)
	v_or_b32_e32 v164, s31, v1
	v_lshl_add_u64 v[130:131], s[14:15], 0, v[130:131]
	v_lshl_or_b32 v165, s2, 8, v1
	s_mov_b32 s7, 0
	s_mov_b64 s[4:5], -1
